# v23: as v22, with group A's two K DMA pieces split across the first two QK MFMA pairs
# speedup vs baseline: 1.0156x; 1.0044x over previous
; #define SBAR() __builtin_amdgcn_sched_barrier(0)
; #define PVR(S, DA, DB, vbase) do { S[0] = tr_read<v_rd_off(DA, 0, 0)>(vbase); S[1] = tr_read<v_rd_off(DA, 0, 1)>(vbase); S[2] = tr_read<v_rd_off(DB, 0, 0)>(vbase); S[3] = tr_read<v_rd_off(DB, 0, 1)>(vbase); \
;     S[4] = tr_read<v_rd_off(DA, 1, 0)>(vbase); S[5] = tr_read<v_rd_off(DA, 1, 1)>(vbase); S[6] = tr_read<v_rd_off(DB, 1, 0)>(vbase); S[7] = tr_read<v_rd_off(DB, 1, 1)>(vbase); } while (0)
; #define RAWBAR() do { asm volatile("s_waitcnt lgkmcnt(0)" ::: "memory"); __builtin_amdgcn_s_barrier(); asm volatile("" ::: "memory"); } while (0)
; #define RAWBAR() do { asm volatile("s_waitcnt lgkmcnt(0)" ::: "memory"); __builtin_amdgcn_s_barrier(); asm volatile("" ::: "memory"); } while (0)
; #define RAWBAR() do { asm volatile("s_waitcnt lgkmcnt(0)" ::: "memory"); __builtin_amdgcn_s_barrier(); asm volatile("" ::: "memory"); } while (0)
; #define RAWBAR() do { asm volatile("s_waitcnt lgkmcnt(0)" ::: "memory"); __builtin_amdgcn_s_barrier(); asm volatile("" ::: "memory"); } while (0)
; #define RAWBAR() do { asm volatile("s_waitcnt lgkmcnt(0)" ::: "memory"); __builtin_amdgcn_s_barrier(); asm volatile("" ::: "memory"); } while (0)
; template <int MODE> ...
;     ...
;   for (int j = 0; j < NT; ++j) {
;     const int buf = j & 1;
;     if (j + 1 < NT) { STAGE((j + 1) * KVBLK, buf ^ 1); }
;     const char* Kb = K_lds + buf * 16384;
;     f32x16 pe = {}, po = {};
; #pragma unroll
;     for (int d0 = 0; d0 < 8; d0 += 2) {
;       const bf16x8 k0 = *reinterpret_cast<const bf16x8*>(Kb + KSWZ(krow, (d0 * 16 + hi * 8) * 2));
;       const bf16x8 k1 = *reinterpret_cast<const bf16x8*>(Kb + KSWZ(krow, ((d0 + 1) * 16 + hi * 8) * 2));
;       pe = __builtin_amdgcn_mfma_f32_32x32x16_bf16(k0, qr[d0], pe, 0, 0, 0);
;       po = __builtin_amdgcn_mfma_f32_32x32x16_bf16(k1, qr[d0 + 1], po, 0, 0, 0); }
;     const int vo = vb0 + buf * 32768;
;     s16x4 R0_[8], R1_[8];
;     PVR(R0_, 0, 1, vo);
;     f32x16 p;
; #pragma unroll
;     for (int r = 0; r < 16; ++r) p[r] = __builtin_amdgcn_exp2f(fmaf(pe[r] + po[r], C, negMc));
;     float ps = 0.f;
; #pragma unroll
;     for (int r = 0; r < 16; ++r) ps += p[r];
;     lsum += ps;
;     const bf16x8 own0 = pk8(p, 0), own1 = pk8(p, 8);
;     SBAR();
;     PV_TAIL4(o, vo, vo + 16384, own0, own1);
;     asm volatile("s_waitcnt vmcnt(0)" ::: "memory");
;     RAWBAR();
;   }
.LBB0_1019:
	ds_read_b128 v[226:229], v225 offset:16384
	ds_read_b128 v[230:233], v223 offset:16384
	ds_read_b128 v[234:237], v222 offset:16384
	ds_read_b128 v[238:241], v221 offset:16384
	v_exp_f32_e32 v144, v144
	v_exp_f32_e32 v145, v145
	v_exp_f32_e32 v146, v146
	v_exp_f32_e32 v147, v147
	s_waitcnt lgkmcnt(2)
	v_mfma_f32_32x32x16_bf16 v[128:143], v[226:229], v[188:191], 0
	v_mfma_f32_32x32x16_bf16 v[128:143], v[230:233], v[184:187], v[128:143]
	ds_read_b128 v[226:229], v202 offset:16384
	ds_read_b128 v[230:233], v203 offset:16384
	s_mov_b32 m0, s24
	s_nop 0
	global_load_lds_dwordx4 v220, s[86:87] sc1
	v_exp_f32_e32 v148, v148
	v_exp_f32_e32 v149, v149
	v_exp_f32_e32 v150, v150
	v_exp_f32_e32 v151, v151
	v_add_f32_e32 v246, v144, v145
	v_add_f32_e32 v246, v146, v246
	v_add_f32_e32 v246, v147, v246
	s_waitcnt lgkmcnt(2)
	v_mfma_f32_32x32x16_bf16 v[128:143], v[234:237], v[180:183], v[128:143]
	v_mfma_f32_32x32x16_bf16 v[128:143], v[238:241], v[176:179], v[128:143]
	ds_read_b128 v[234:237], v204 offset:16384
	ds_read_b128 v[238:241], v205 offset:16384
	s_add_i32 m0, s24, 0x2000
	s_nop 0
	global_load_lds_dwordx4 v219, s[86:87] sc1
	v_exp_f32_e32 v152, v152
	v_exp_f32_e32 v153, v153
	v_exp_f32_e32 v154, v154
	v_exp_f32_e32 v155, v155
	v_add_f32_e32 v246, v148, v246
	v_add_f32_e32 v246, v149, v246
	v_add_f32_e32 v246, v150, v246
	v_add_f32_e32 v246, v151, v246
	s_waitcnt lgkmcnt(2)
	v_mfma_f32_32x32x16_bf16 v[128:143], v[226:229], v[172:175], v[128:143]
	v_mfma_f32_32x32x16_bf16 v[128:143], v[230:233], v[168:171], v[128:143]
	v_exp_f32_e32 v156, v156
	v_exp_f32_e32 v157, v157
	v_exp_f32_e32 v158, v158
	v_exp_f32_e32 v159, v159
	v_add_f32_e32 v246, v152, v246
	v_add_f32_e32 v246, v153, v246
	v_add_f32_e32 v246, v154, v246
	v_add_f32_e32 v246, v155, v246
	v_cvt_pk_bf16_f32 v226, v144, v145
	v_cvt_pk_bf16_f32 v227, v146, v147
	v_cvt_pk_bf16_f32 v228, v148, v149
	v_cvt_pk_bf16_f32 v229, v150, v151
	s_waitcnt lgkmcnt(0)
	v_mfma_f32_32x32x16_bf16 v[128:143], v[234:237], v[164:167], v[128:143]
	v_mfma_f32_32x32x16_bf16 v[128:143], v[238:241], v[160:163], v[128:143]
	v_add_u32_e32 v245, s84, v214
	s_add_i32 s85, s84, 0x8000
	s_cmp_eq_u32 s85, 0x18000
	s_cselect_b32 s85, 0, s85
	ds_read_b64_tr_b16 v[234:235], v245 offset:0
	ds_read_b64_tr_b16 v[236:237], v245 offset:2048
	ds_read_b64_tr_b16 v[238:239], v245 offset:512
	ds_read_b64_tr_b16 v[240:241], v245 offset:2560
	ds_read_b64_tr_b16 v[144:145], v245 offset:4096
	ds_read_b64_tr_b16 v[146:147], v245 offset:6144
	ds_read_b64_tr_b16 v[148:149], v245 offset:4608
	ds_read_b64_tr_b16 v[150:151], v245 offset:6656
	v_add_f32_e32 v246, v156, v246
	v_add_f32_e32 v246, v157, v246
	v_add_f32_e32 v246, v158, v246
	v_add_f32_e32 v246, v159, v246
	v_cvt_pk_bf16_f32 v230, v152, v153
	v_cvt_pk_bf16_f32 v231, v154, v155
	v_cvt_pk_bf16_f32 v232, v156, v157
	v_cvt_pk_bf16_f32 v233, v158, v159
	v_add_f32_e32 v215, v215, v246
	ds_read_b64_tr_b16 v[152:153], v245 offset:1024
	ds_read_b64_tr_b16 v[154:155], v245 offset:3072
	ds_read_b64_tr_b16 v[156:157], v245 offset:1536
	ds_read_b64_tr_b16 v[158:159], v245 offset:3584
	s_waitcnt lgkmcnt(8)
	v_mfma_f32_32x32x16_bf16 v[112:127], v[226:229], v[234:237], v[112:127]
	v_mfma_f32_32x32x16_bf16 v[96:111], v[226:229], v[238:241], v[96:111]
	ds_read_b64_tr_b16 v[234:235], v245 offset:5120
	ds_read_b64_tr_b16 v[236:237], v245 offset:7168
	ds_read_b64_tr_b16 v[238:239], v245 offset:5632
	ds_read_b64_tr_b16 v[240:241], v245 offset:7680
	s_add_i32 s41, s85, s24
	s_add_i32 m0, s41, 0x8000
	s_nop 0
	global_load_lds_dwordx4 v218, s[2:3] sc1
	s_waitcnt lgkmcnt(8)
	v_mfma_f32_32x32x16_bf16 v[112:127], v[230:233], v[144:147], v[112:127]
	v_mfma_f32_32x32x16_bf16 v[96:111], v[230:233], v[148:151], v[96:111]
	ds_read_b64_tr_b16 v[144:145], v245 offset:16384
	ds_read_b64_tr_b16 v[146:147], v245 offset:18432
	ds_read_b64_tr_b16 v[148:149], v245 offset:16896
	ds_read_b64_tr_b16 v[150:151], v245 offset:18944
	s_add_i32 s41, s85, s24
	s_add_i32 m0, s41, 0xa000
	s_nop 0
	global_load_lds_dwordx4 v217, s[2:3] sc1
	s_waitcnt lgkmcnt(8)
	v_mfma_f32_32x32x16_bf16 v[80:95], v[226:229], v[152:155], v[80:95]
	v_mfma_f32_32x32x16_bf16 v[64:79], v[226:229], v[156:159], v[64:79]
	ds_read_b64_tr_b16 v[152:153], v245 offset:20480
	ds_read_b64_tr_b16 v[154:155], v245 offset:22528
	ds_read_b64_tr_b16 v[156:157], v245 offset:20992
	ds_read_b64_tr_b16 v[158:159], v245 offset:23040
	s_add_i32 s41, s85, s24
	s_add_i32 m0, s41, 0xc000
	s_nop 0
	global_load_lds_dwordx4 v242, s[2:3] sc1
	s_waitcnt lgkmcnt(8)
	v_mfma_f32_32x32x16_bf16 v[80:95], v[230:233], v[234:237], v[80:95]
	v_mfma_f32_32x32x16_bf16 v[64:79], v[230:233], v[238:241], v[64:79]
	ds_read_b64_tr_b16 v[234:235], v245 offset:17408
	ds_read_b64_tr_b16 v[236:237], v245 offset:19456
	ds_read_b64_tr_b16 v[238:239], v245 offset:17920
	ds_read_b64_tr_b16 v[240:241], v245 offset:19968
	s_add_i32 s41, s85, s24
	s_add_i32 m0, s41, 0xe000
	s_nop 0
	global_load_lds_dwordx4 v243, s[2:3] sc1
	s_waitcnt lgkmcnt(8)
	v_mfma_f32_32x32x16_bf16 v[48:63], v[226:229], v[144:147], v[48:63]
	v_mfma_f32_32x32x16_bf16 v[32:47], v[226:229], v[148:151], v[32:47]
	ds_read_b64_tr_b16 v[144:145], v245 offset:21504
	ds_read_b64_tr_b16 v[146:147], v245 offset:23552
	ds_read_b64_tr_b16 v[148:149], v245 offset:22016
	ds_read_b64_tr_b16 v[150:151], v245 offset:24064
	s_waitcnt lgkmcnt(8)
	v_mfma_f32_32x32x16_bf16 v[48:63], v[230:233], v[152:155], v[48:63]
	v_mfma_f32_32x32x16_bf16 v[32:47], v[230:233], v[156:159], v[32:47]
	s_waitcnt lgkmcnt(0)
	v_mfma_f32_32x32x16_bf16 v[16:31], v[226:229], v[234:237], v[16:31]
	s_waitcnt vmcnt(0)
	s_barrier
; #define SBAR() __builtin_amdgcn_sched_barrier(0)
; #define PVR(S, DA, DB, vbase) do { S[0] = tr_read<v_rd_off(DA, 0, 0)>(vbase); S[1] = tr_read<v_rd_off(DA, 0, 1)>(vbase); S[2] = tr_read<v_rd_off(DB, 0, 0)>(vbase); S[3] = tr_read<v_rd_off(DB, 0, 1)>(vbase); \
;     S[4] = tr_read<v_rd_off(DA, 1, 0)>(vbase); S[5] = tr_read<v_rd_off(DA, 1, 1)>(vbase); S[6] = tr_read<v_rd_off(DB, 1, 0)>(vbase); S[7] = tr_read<v_rd_off(DB, 1, 1)>(vbase); } while (0)
; #define RAWBAR() do { asm volatile("s_waitcnt lgkmcnt(0)" ::: "memory"); __builtin_amdgcn_s_barrier(); asm volatile("" ::: "memory"); } while (0)
; #define RAWBAR() do { asm volatile("s_waitcnt lgkmcnt(0)" ::: "memory"); __builtin_amdgcn_s_barrier(); asm volatile("" ::: "memory"); } while (0)
; #define RAWBAR() do { asm volatile("s_waitcnt lgkmcnt(0)" ::: "memory"); __builtin_amdgcn_s_barrier(); asm volatile("" ::: "memory"); } while (0)
; #define RAWBAR() do { asm volatile("s_waitcnt lgkmcnt(0)" ::: "memory"); __builtin_amdgcn_s_barrier(); asm volatile("" ::: "memory"); } while (0)
; #define RAWBAR() do { asm volatile("s_waitcnt lgkmcnt(0)" ::: "memory"); __builtin_amdgcn_s_barrier(); asm volatile("" ::: "memory"); } while (0)
; template <int MODE> ...
;     ...
;   for (int j = 0; j < NT; ++j) {
;     const int buf = j & 1;
;     if (j + 1 < NT) { STAGE((j + 1) * KVBLK, buf ^ 1); }
;     const char* Kb = K_lds + buf * 16384;
;     f32x16 pe = {}, po = {};
; #pragma unroll
;     for (int d0 = 0; d0 < 8; d0 += 2) {
;       const bf16x8 k0 = *reinterpret_cast<const bf16x8*>(Kb + KSWZ(krow, (d0 * 16 + hi * 8) * 2));
;       const bf16x8 k1 = *reinterpret_cast<const bf16x8*>(Kb + KSWZ(krow, ((d0 + 1) * 16 + hi * 8) * 2));
;       pe = __builtin_amdgcn_mfma_f32_32x32x16_bf16(k0, qr[d0], pe, 0, 0, 0);
;       po = __builtin_amdgcn_mfma_f32_32x32x16_bf16(k1, qr[d0 + 1], po, 0, 0, 0); }
;     const int vo = vb0 + buf * 32768;
;     s16x4 R0_[8], R1_[8];
;     PVR(R0_, 0, 1, vo);
;     f32x16 p;
; #pragma unroll
;     for (int r = 0; r < 16; ++r) p[r] = __builtin_amdgcn_exp2f(fmaf(pe[r] + po[r], C, negMc));
;     float ps = 0.f;
; #pragma unroll
;     for (int r = 0; r < 16; ++r) ps += p[r];
;     lsum += ps;
;     const bf16x8 own0 = pk8(p, 0), own1 = pk8(p, 8);
;     SBAR();
;     PV_TAIL4(o, vo, vo + 16384, own0, own1);
;     asm volatile("s_waitcnt vmcnt(0)" ::: "memory");
;     RAWBAR();
;   }
	s_add_u32 s86, s86, 0x4000
	s_addc_u32 s87, s87, 0
	s_add_u32 s2, s2, 0x8000
	s_addc_u32 s3, s3, 0
	v_mfma_f32_32x32x16_bf16 v[0:15], v[226:229], v[238:241], v[0:15]
	v_mfma_f32_32x32x16_bf16 v[16:31], v[230:233], v[144:147], v[16:31]
	v_mfma_f32_32x32x16_bf16 v[0:15], v[230:233], v[148:151], v[0:15]
	s_add_i32 s84, s84, 0x8000
	s_cmp_eq_u32 s84, 0x18000
	s_cselect_b32 s84, 0, s84
	ds_read_b128 v[226:229], v225 offset:0
	ds_read_b128 v[230:233], v223 offset:0
	ds_read_b128 v[234:237], v222 offset:0
	ds_read_b128 v[238:241], v221 offset:0
	v_exp_f32_e32 v128, v128
	v_exp_f32_e32 v129, v129
	v_exp_f32_e32 v130, v130
	v_exp_f32_e32 v131, v131
	s_waitcnt lgkmcnt(2)
	v_mfma_f32_32x32x16_bf16 v[144:159], v[226:229], v[188:191], 0
	v_mfma_f32_32x32x16_bf16 v[144:159], v[230:233], v[184:187], v[144:159]
	ds_read_b128 v[226:229], v202 offset:0
	ds_read_b128 v[230:233], v203 offset:0
	s_add_i32 m0, s24, 0x4000
	s_nop 0
	global_load_lds_dwordx4 v220, s[86:87] sc1
	v_exp_f32_e32 v132, v132
	v_exp_f32_e32 v133, v133
	v_exp_f32_e32 v134, v134
	v_exp_f32_e32 v135, v135
	v_add_f32_e32 v246, v128, v129
	v_add_f32_e32 v246, v130, v246
	v_add_f32_e32 v246, v131, v246
	s_waitcnt lgkmcnt(2)
	v_mfma_f32_32x32x16_bf16 v[144:159], v[234:237], v[180:183], v[144:159]
	v_mfma_f32_32x32x16_bf16 v[144:159], v[238:241], v[176:179], v[144:159]
	ds_read_b128 v[234:237], v204 offset:0
	ds_read_b128 v[238:241], v205 offset:0
	s_add_i32 m0, s24, 0x6000
	s_nop 0
	global_load_lds_dwordx4 v219, s[86:87] sc1
	v_exp_f32_e32 v136, v136
	v_exp_f32_e32 v137, v137
	v_exp_f32_e32 v138, v138
	v_exp_f32_e32 v139, v139
	v_add_f32_e32 v246, v132, v246
	v_add_f32_e32 v246, v133, v246
	v_add_f32_e32 v246, v134, v246
	v_add_f32_e32 v246, v135, v246
	s_waitcnt lgkmcnt(2)
	v_mfma_f32_32x32x16_bf16 v[144:159], v[226:229], v[172:175], v[144:159]
	v_mfma_f32_32x32x16_bf16 v[144:159], v[230:233], v[168:171], v[144:159]
	v_exp_f32_e32 v140, v140
	v_exp_f32_e32 v141, v141
	v_exp_f32_e32 v142, v142
	v_exp_f32_e32 v143, v143
	v_add_f32_e32 v246, v136, v246
	v_add_f32_e32 v246, v137, v246
	v_add_f32_e32 v246, v138, v246
	v_add_f32_e32 v246, v139, v246
	v_cvt_pk_bf16_f32 v226, v128, v129
	v_cvt_pk_bf16_f32 v227, v130, v131
	v_cvt_pk_bf16_f32 v228, v132, v133
	v_cvt_pk_bf16_f32 v229, v134, v135
	s_waitcnt lgkmcnt(0)
	v_mfma_f32_32x32x16_bf16 v[144:159], v[234:237], v[164:167], v[144:159]
	v_mfma_f32_32x32x16_bf16 v[144:159], v[238:241], v[160:163], v[144:159]
	v_add_u32_e32 v245, s84, v214
	s_add_i32 s85, s84, 0x8000
	s_cmp_eq_u32 s85, 0x18000
	s_cselect_b32 s85, 0, s85
	ds_read_b64_tr_b16 v[234:235], v245 offset:0
	ds_read_b64_tr_b16 v[236:237], v245 offset:2048
	ds_read_b64_tr_b16 v[238:239], v245 offset:512
	ds_read_b64_tr_b16 v[240:241], v245 offset:2560
	ds_read_b64_tr_b16 v[128:129], v245 offset:4096
	ds_read_b64_tr_b16 v[130:131], v245 offset:6144
	ds_read_b64_tr_b16 v[132:133], v245 offset:4608
	ds_read_b64_tr_b16 v[134:135], v245 offset:6656
	v_add_f32_e32 v246, v140, v246
	v_add_f32_e32 v246, v141, v246
	v_add_f32_e32 v246, v142, v246
	v_add_f32_e32 v246, v143, v246
	v_cvt_pk_bf16_f32 v230, v136, v137
	v_cvt_pk_bf16_f32 v231, v138, v139
	v_cvt_pk_bf16_f32 v232, v140, v141
	v_cvt_pk_bf16_f32 v233, v142, v143
	v_add_f32_e32 v215, v215, v246
	ds_read_b64_tr_b16 v[136:137], v245 offset:1024
	ds_read_b64_tr_b16 v[138:139], v245 offset:3072
	ds_read_b64_tr_b16 v[140:141], v245 offset:1536
	ds_read_b64_tr_b16 v[142:143], v245 offset:3584
	s_waitcnt lgkmcnt(8)
	v_mfma_f32_32x32x16_bf16 v[112:127], v[226:229], v[234:237], v[112:127]
	v_mfma_f32_32x32x16_bf16 v[96:111], v[226:229], v[238:241], v[96:111]
	ds_read_b64_tr_b16 v[234:235], v245 offset:5120
	ds_read_b64_tr_b16 v[236:237], v245 offset:7168
	ds_read_b64_tr_b16 v[238:239], v245 offset:5632
	ds_read_b64_tr_b16 v[240:241], v245 offset:7680
	s_add_i32 s41, s85, s24
	s_add_i32 m0, s41, 0x8000
	s_nop 0
	global_load_lds_dwordx4 v218, s[2:3] sc1
	s_waitcnt lgkmcnt(8)
	v_mfma_f32_32x32x16_bf16 v[112:127], v[230:233], v[128:131], v[112:127]
	v_mfma_f32_32x32x16_bf16 v[96:111], v[230:233], v[132:135], v[96:111]
	ds_read_b64_tr_b16 v[128:129], v245 offset:16384
	ds_read_b64_tr_b16 v[130:131], v245 offset:18432
	ds_read_b64_tr_b16 v[132:133], v245 offset:16896
	ds_read_b64_tr_b16 v[134:135], v245 offset:18944
	s_add_i32 s41, s85, s24
	s_add_i32 m0, s41, 0xa000
	s_nop 0
	global_load_lds_dwordx4 v217, s[2:3] sc1
	s_waitcnt lgkmcnt(8)
	v_mfma_f32_32x32x16_bf16 v[80:95], v[226:229], v[136:139], v[80:95]
	v_mfma_f32_32x32x16_bf16 v[64:79], v[226:229], v[140:143], v[64:79]
	ds_read_b64_tr_b16 v[136:137], v245 offset:20480
	ds_read_b64_tr_b16 v[138:139], v245 offset:22528
	ds_read_b64_tr_b16 v[140:141], v245 offset:20992
	ds_read_b64_tr_b16 v[142:143], v245 offset:23040
	s_add_i32 s41, s85, s24
	s_add_i32 m0, s41, 0xc000
	s_nop 0
	global_load_lds_dwordx4 v242, s[2:3] sc1
	s_waitcnt lgkmcnt(8)
	v_mfma_f32_32x32x16_bf16 v[80:95], v[230:233], v[234:237], v[80:95]
	v_mfma_f32_32x32x16_bf16 v[64:79], v[230:233], v[238:241], v[64:79]
	ds_read_b64_tr_b16 v[234:235], v245 offset:17408
	ds_read_b64_tr_b16 v[236:237], v245 offset:19456
	ds_read_b64_tr_b16 v[238:239], v245 offset:17920
	ds_read_b64_tr_b16 v[240:241], v245 offset:19968
	s_add_i32 s41, s85, s24
	s_add_i32 m0, s41, 0xe000
	s_nop 0
	global_load_lds_dwordx4 v243, s[2:3] sc1
	s_waitcnt lgkmcnt(8)
	v_mfma_f32_32x32x16_bf16 v[48:63], v[226:229], v[128:131], v[48:63]
	v_mfma_f32_32x32x16_bf16 v[32:47], v[226:229], v[132:135], v[32:47]
	ds_read_b64_tr_b16 v[128:129], v245 offset:21504
	ds_read_b64_tr_b16 v[130:131], v245 offset:23552
	ds_read_b64_tr_b16 v[132:133], v245 offset:22016
	ds_read_b64_tr_b16 v[134:135], v245 offset:24064
	s_waitcnt lgkmcnt(8)
	v_mfma_f32_32x32x16_bf16 v[48:63], v[230:233], v[136:139], v[48:63]
	v_mfma_f32_32x32x16_bf16 v[32:47], v[230:233], v[140:143], v[32:47]
	s_waitcnt lgkmcnt(0)
	v_mfma_f32_32x32x16_bf16 v[16:31], v[226:229], v[234:237], v[16:31]
	s_waitcnt vmcnt(0)
	s_barrier
	s_add_u32 s86, s86, 0x4000
	s_addc_u32 s87, s87, 0
	s_add_u32 s2, s2, 0x8000
	s_addc_u32 s3, s3, 0
	v_mfma_f32_32x32x16_bf16 v[0:15], v[226:229], v[238:241], v[0:15]
	v_mfma_f32_32x32x16_bf16 v[16:31], v[230:233], v[128:131], v[16:31]
	v_mfma_f32_32x32x16_bf16 v[0:15], v[230:233], v[132:135], v[0:15]
	s_add_i32 s84, s84, 0x8000
	s_cmp_eq_u32 s84, 0x18000
	s_cselect_b32 s84, 0, s84
	s_add_i32 s25, s25, 1
	s_cmpk_eq_i32 s25, 0x82
	s_cbranch_scc0 .LBB0_1019
	s_barrier
	s_branch .Lattn_join_m0

; #define SBAR() __builtin_amdgcn_sched_barrier(0)
; #define PVR(S, DA, DB, vbase) do { S[0] = tr_read<v_rd_off(DA, 0, 0)>(vbase); S[1] = tr_read<v_rd_off(DA, 0, 1)>(vbase); S[2] = tr_read<v_rd_off(DB, 0, 0)>(vbase); S[3] = tr_read<v_rd_off(DB, 0, 1)>(vbase); \
;     S[4] = tr_read<v_rd_off(DA, 1, 0)>(vbase); S[5] = tr_read<v_rd_off(DA, 1, 1)>(vbase); S[6] = tr_read<v_rd_off(DB, 1, 0)>(vbase); S[7] = tr_read<v_rd_off(DB, 1, 1)>(vbase); } while (0)
; #define RAWBAR() do { asm volatile("s_waitcnt lgkmcnt(0)" ::: "memory"); __builtin_amdgcn_s_barrier(); asm volatile("" ::: "memory"); } while (0)
; #define RAWBAR() do { asm volatile("s_waitcnt lgkmcnt(0)" ::: "memory"); __builtin_amdgcn_s_barrier(); asm volatile("" ::: "memory"); } while (0)
; #define RAWBAR() do { asm volatile("s_waitcnt lgkmcnt(0)" ::: "memory"); __builtin_amdgcn_s_barrier(); asm volatile("" ::: "memory"); } while (0)
; #define RAWBAR() do { asm volatile("s_waitcnt lgkmcnt(0)" ::: "memory"); __builtin_amdgcn_s_barrier(); asm volatile("" ::: "memory"); } while (0)
; #define RAWBAR() do { asm volatile("s_waitcnt lgkmcnt(0)" ::: "memory"); __builtin_amdgcn_s_barrier(); asm volatile("" ::: "memory"); } while (0)
; template <int MODE> ...
;     ...
;   for (int j = 0; j < NT; ++j) {
;     const int buf = j & 1;
;     if (j + 1 < NT) { STAGE((j + 1) * KVBLK, buf ^ 1); }
;     const char* Kb = K_lds + buf * 16384;
;     f32x16 pe = {}, po = {};
; #pragma unroll
;     for (int d0 = 0; d0 < 8; d0 += 2) {
;       const bf16x8 k0 = *reinterpret_cast<const bf16x8*>(Kb + KSWZ(krow, (d0 * 16 + hi * 8) * 2));
;       const bf16x8 k1 = *reinterpret_cast<const bf16x8*>(Kb + KSWZ(krow, ((d0 + 1) * 16 + hi * 8) * 2));
;       pe = __builtin_amdgcn_mfma_f32_32x32x16_bf16(k0, qr[d0], pe, 0, 0, 0);
;       po = __builtin_amdgcn_mfma_f32_32x32x16_bf16(k1, qr[d0 + 1], po, 0, 0, 0); }
;     const int vo = vb0 + buf * 32768;
;     s16x4 R0_[8], R1_[8];
;     PVR(R0_, 0, 1, vo);
;     f32x16 p;
; #pragma unroll
;     for (int r = 0; r < 16; ++r) p[r] = __builtin_amdgcn_exp2f(fmaf(pe[r] + po[r], C, negMc));
;     float ps = 0.f;
; #pragma unroll
;     for (int r = 0; r < 16; ++r) ps += p[r];
;     lsum += ps;
;     const bf16x8 own0 = pk8(p, 0), own1 = pk8(p, 8);
;     SBAR();
;     PV_TAIL4(o, vo, vo + 16384, own0, own1);
;     asm volatile("s_waitcnt vmcnt(0)" ::: "memory");
;     RAWBAR();
;   }
.LBB0_1023:
	ds_read_b128 v[230:233], v229 offset:16384
	ds_read_b128 v[234:237], v228 offset:16384
	ds_read_b128 v[238:241], v227 offset:16384
	ds_read_b128 v[242:245], v226 offset:16384
	v_exp_f32_e32 v144, v144
	v_exp_f32_e32 v145, v145
	v_exp_f32_e32 v146, v146
	v_exp_f32_e32 v147, v147
	s_waitcnt lgkmcnt(2)
	v_mfma_f32_32x32x16_bf16 v[128:143], v[230:233], v[188:191], 0
	v_mfma_f32_32x32x16_bf16 v[128:143], v[234:237], v[184:187], v[128:143]
	ds_read_b128 v[230:233], v204 offset:16384
	ds_read_b128 v[234:237], v205 offset:16384
	s_mov_b32 m0, s34
	s_nop 0
	global_load_lds_dwordx4 v225, s[86:87] sc1
	v_exp_f32_e32 v148, v148
	v_exp_f32_e32 v149, v149
	v_exp_f32_e32 v150, v150
	v_exp_f32_e32 v151, v151
	v_add_f32_e32 v250, v144, v145
	v_add_f32_e32 v250, v146, v250
	v_add_f32_e32 v250, v147, v250
	s_waitcnt lgkmcnt(2)
	v_mfma_f32_32x32x16_bf16 v[128:143], v[238:241], v[180:183], v[128:143]
	v_mfma_f32_32x32x16_bf16 v[128:143], v[242:245], v[176:179], v[128:143]
	ds_read_b128 v[238:241], v206 offset:16384
	ds_read_b128 v[242:245], v207 offset:16384
	s_add_i32 m0, s34, 0x2000
	s_nop 0
	global_load_lds_dwordx4 v223, s[86:87] sc1
	v_exp_f32_e32 v152, v152
	v_exp_f32_e32 v153, v153
	v_exp_f32_e32 v154, v154
	v_exp_f32_e32 v155, v155
	v_add_f32_e32 v250, v148, v250
	v_add_f32_e32 v250, v149, v250
	v_add_f32_e32 v250, v150, v250
	v_add_f32_e32 v250, v151, v250
	s_waitcnt lgkmcnt(2)
	v_mfma_f32_32x32x16_bf16 v[128:143], v[230:233], v[172:175], v[128:143]
	v_mfma_f32_32x32x16_bf16 v[128:143], v[234:237], v[168:171], v[128:143]
	v_exp_f32_e32 v156, v156
	v_exp_f32_e32 v157, v157
	v_exp_f32_e32 v158, v158
	v_exp_f32_e32 v159, v159
	v_add_f32_e32 v250, v152, v250
	v_add_f32_e32 v250, v153, v250
	v_add_f32_e32 v250, v154, v250
	v_add_f32_e32 v250, v155, v250
	v_cvt_pk_bf16_f32 v230, v144, v145
	v_cvt_pk_bf16_f32 v231, v146, v147
	v_cvt_pk_bf16_f32 v232, v148, v149
	v_cvt_pk_bf16_f32 v233, v150, v151
	s_waitcnt lgkmcnt(0)
	v_mfma_f32_32x32x16_bf16 v[128:143], v[238:241], v[164:167], v[128:143]
	v_mfma_f32_32x32x16_bf16 v[128:143], v[242:245], v[160:163], v[128:143]
	v_add_u32_e32 v249, s84, v218
	s_add_i32 s85, s84, 0x8000
	s_cmp_eq_u32 s85, 0x18000
	s_cselect_b32 s85, 0, s85
	ds_read_b64_tr_b16 v[238:239], v249 offset:0
	ds_read_b64_tr_b16 v[240:241], v249 offset:2048
	ds_read_b64_tr_b16 v[242:243], v249 offset:512
	ds_read_b64_tr_b16 v[244:245], v249 offset:2560
	ds_read_b64_tr_b16 v[144:145], v249 offset:4096
	ds_read_b64_tr_b16 v[146:147], v249 offset:6144
	ds_read_b64_tr_b16 v[148:149], v249 offset:4608
	ds_read_b64_tr_b16 v[150:151], v249 offset:6656
	v_add_f32_e32 v250, v156, v250
	v_add_f32_e32 v250, v157, v250
	v_add_f32_e32 v250, v158, v250
	v_add_f32_e32 v250, v159, v250
	v_cvt_pk_bf16_f32 v234, v152, v153
	v_cvt_pk_bf16_f32 v235, v154, v155
	v_cvt_pk_bf16_f32 v236, v156, v157
	v_cvt_pk_bf16_f32 v237, v158, v159
	v_add_f32_e32 v219, v219, v250
	ds_read_b64_tr_b16 v[152:153], v249 offset:1024
	ds_read_b64_tr_b16 v[154:155], v249 offset:3072
	ds_read_b64_tr_b16 v[156:157], v249 offset:1536
	ds_read_b64_tr_b16 v[158:159], v249 offset:3584
	s_waitcnt lgkmcnt(8)
	v_mfma_f32_32x32x16_bf16 v[112:127], v[230:233], v[238:241], v[112:127]
	v_mfma_f32_32x32x16_bf16 v[96:111], v[230:233], v[242:245], v[96:111]
	ds_read_b64_tr_b16 v[238:239], v249 offset:5120
	ds_read_b64_tr_b16 v[240:241], v249 offset:7168
	ds_read_b64_tr_b16 v[242:243], v249 offset:5632
	ds_read_b64_tr_b16 v[244:245], v249 offset:7680
	s_add_i32 s30, s85, s34
	s_add_i32 m0, s30, 0x8000
	s_nop 0
	global_load_lds_dwordx4 v222, s[2:3] sc1
	s_waitcnt lgkmcnt(8)
	v_mfma_f32_32x32x16_bf16 v[112:127], v[234:237], v[144:147], v[112:127]
	v_mfma_f32_32x32x16_bf16 v[96:111], v[234:237], v[148:151], v[96:111]
	ds_read_b64_tr_b16 v[144:145], v249 offset:16384
	ds_read_b64_tr_b16 v[146:147], v249 offset:18432
	ds_read_b64_tr_b16 v[148:149], v249 offset:16896
	ds_read_b64_tr_b16 v[150:151], v249 offset:18944
	s_add_i32 s30, s85, s34
	s_add_i32 m0, s30, 0xa000
	s_nop 0
	global_load_lds_dwordx4 v221, s[2:3] sc1
	s_waitcnt lgkmcnt(8)
	v_mfma_f32_32x32x16_bf16 v[80:95], v[230:233], v[152:155], v[80:95]
	v_mfma_f32_32x32x16_bf16 v[64:79], v[230:233], v[156:159], v[64:79]
	ds_read_b64_tr_b16 v[152:153], v249 offset:20480
	ds_read_b64_tr_b16 v[154:155], v249 offset:22528
	ds_read_b64_tr_b16 v[156:157], v249 offset:20992
	ds_read_b64_tr_b16 v[158:159], v249 offset:23040
	s_add_i32 s30, s85, s34
	s_add_i32 m0, s30, 0xc000
	s_nop 0
	global_load_lds_dwordx4 v246, s[2:3] sc1
	s_waitcnt lgkmcnt(8)
	v_mfma_f32_32x32x16_bf16 v[80:95], v[234:237], v[238:241], v[80:95]
	v_mfma_f32_32x32x16_bf16 v[64:79], v[234:237], v[242:245], v[64:79]
	ds_read_b64_tr_b16 v[238:239], v249 offset:17408
	ds_read_b64_tr_b16 v[240:241], v249 offset:19456
	ds_read_b64_tr_b16 v[242:243], v249 offset:17920
	ds_read_b64_tr_b16 v[244:245], v249 offset:19968
	s_add_i32 s30, s85, s34
	s_add_i32 m0, s30, 0xe000
	s_nop 0
	global_load_lds_dwordx4 v247, s[2:3] sc1
	s_waitcnt lgkmcnt(8)
	v_mfma_f32_32x32x16_bf16 v[32:47], v[230:233], v[144:147], v[32:47]
	v_mfma_f32_32x32x16_bf16 v[16:31], v[230:233], v[148:151], v[16:31]
	ds_read_b64_tr_b16 v[144:145], v249 offset:21504
	ds_read_b64_tr_b16 v[146:147], v249 offset:23552
	ds_read_b64_tr_b16 v[148:149], v249 offset:22016
	ds_read_b64_tr_b16 v[150:151], v249 offset:24064
	s_waitcnt lgkmcnt(8)
	v_mfma_f32_32x32x16_bf16 v[32:47], v[234:237], v[152:155], v[32:47]
	v_mfma_f32_32x32x16_bf16 v[16:31], v[234:237], v[156:159], v[16:31]
	s_waitcnt lgkmcnt(0)
	v_mfma_f32_32x32x16_bf16 v[48:63], v[230:233], v[238:241], v[48:63]
	s_waitcnt vmcnt(0)
	s_barrier
; #define SBAR() __builtin_amdgcn_sched_barrier(0)
; #define PVR(S, DA, DB, vbase) do { S[0] = tr_read<v_rd_off(DA, 0, 0)>(vbase); S[1] = tr_read<v_rd_off(DA, 0, 1)>(vbase); S[2] = tr_read<v_rd_off(DB, 0, 0)>(vbase); S[3] = tr_read<v_rd_off(DB, 0, 1)>(vbase); \
;     S[4] = tr_read<v_rd_off(DA, 1, 0)>(vbase); S[5] = tr_read<v_rd_off(DA, 1, 1)>(vbase); S[6] = tr_read<v_rd_off(DB, 1, 0)>(vbase); S[7] = tr_read<v_rd_off(DB, 1, 1)>(vbase); } while (0)
; #define RAWBAR() do { asm volatile("s_waitcnt lgkmcnt(0)" ::: "memory"); __builtin_amdgcn_s_barrier(); asm volatile("" ::: "memory"); } while (0)
; #define RAWBAR() do { asm volatile("s_waitcnt lgkmcnt(0)" ::: "memory"); __builtin_amdgcn_s_barrier(); asm volatile("" ::: "memory"); } while (0)
; #define RAWBAR() do { asm volatile("s_waitcnt lgkmcnt(0)" ::: "memory"); __builtin_amdgcn_s_barrier(); asm volatile("" ::: "memory"); } while (0)
; #define RAWBAR() do { asm volatile("s_waitcnt lgkmcnt(0)" ::: "memory"); __builtin_amdgcn_s_barrier(); asm volatile("" ::: "memory"); } while (0)
; #define RAWBAR() do { asm volatile("s_waitcnt lgkmcnt(0)" ::: "memory"); __builtin_amdgcn_s_barrier(); asm volatile("" ::: "memory"); } while (0)
; template <int MODE> ...
;     ...
;   for (int j = 0; j < NT; ++j) {
;     const int buf = j & 1;
;     if (j + 1 < NT) { STAGE((j + 1) * KVBLK, buf ^ 1); }
;     const char* Kb = K_lds + buf * 16384;
;     f32x16 pe = {}, po = {};
; #pragma unroll
;     for (int d0 = 0; d0 < 8; d0 += 2) {
;       const bf16x8 k0 = *reinterpret_cast<const bf16x8*>(Kb + KSWZ(krow, (d0 * 16 + hi * 8) * 2));
;       const bf16x8 k1 = *reinterpret_cast<const bf16x8*>(Kb + KSWZ(krow, ((d0 + 1) * 16 + hi * 8) * 2));
;       pe = __builtin_amdgcn_mfma_f32_32x32x16_bf16(k0, qr[d0], pe, 0, 0, 0);
;       po = __builtin_amdgcn_mfma_f32_32x32x16_bf16(k1, qr[d0 + 1], po, 0, 0, 0); }
;     const int vo = vb0 + buf * 32768;
;     s16x4 R0_[8], R1_[8];
;     PVR(R0_, 0, 1, vo);
;     f32x16 p;
; #pragma unroll
;     for (int r = 0; r < 16; ++r) p[r] = __builtin_amdgcn_exp2f(fmaf(pe[r] + po[r], C, negMc));
;     float ps = 0.f;
; #pragma unroll
;     for (int r = 0; r < 16; ++r) ps += p[r];
;     lsum += ps;
;     const bf16x8 own0 = pk8(p, 0), own1 = pk8(p, 8);
;     SBAR();
;     PV_TAIL4(o, vo, vo + 16384, own0, own1);
;     asm volatile("s_waitcnt vmcnt(0)" ::: "memory");
;     RAWBAR();
;   }
	s_add_u32 s86, s86, 0x4000
	s_addc_u32 s87, s87, 0
	s_add_u32 s2, s2, 0x8000
	s_addc_u32 s3, s3, 0
	v_mfma_f32_32x32x16_bf16 v[0:15], v[230:233], v[242:245], v[0:15]
	v_mfma_f32_32x32x16_bf16 v[48:63], v[234:237], v[144:147], v[48:63]
	v_mfma_f32_32x32x16_bf16 v[0:15], v[234:237], v[148:151], v[0:15]
	s_add_i32 s84, s84, 0x8000
	s_cmp_eq_u32 s84, 0x18000
	s_cselect_b32 s84, 0, s84
	ds_read_b128 v[230:233], v229 offset:0
	ds_read_b128 v[234:237], v228 offset:0
	ds_read_b128 v[238:241], v227 offset:0
	ds_read_b128 v[242:245], v226 offset:0
	v_exp_f32_e32 v128, v128
	v_exp_f32_e32 v129, v129
	v_exp_f32_e32 v130, v130
	v_exp_f32_e32 v131, v131
	s_waitcnt lgkmcnt(2)
	v_mfma_f32_32x32x16_bf16 v[144:159], v[230:233], v[188:191], 0
	v_mfma_f32_32x32x16_bf16 v[144:159], v[234:237], v[184:187], v[144:159]
	ds_read_b128 v[230:233], v204 offset:0
	ds_read_b128 v[234:237], v205 offset:0
	s_add_i32 m0, s34, 0x4000
	s_nop 0
	global_load_lds_dwordx4 v225, s[86:87] sc1
	v_exp_f32_e32 v132, v132
	v_exp_f32_e32 v133, v133
	v_exp_f32_e32 v134, v134
	v_exp_f32_e32 v135, v135
	v_add_f32_e32 v250, v128, v129
	v_add_f32_e32 v250, v130, v250
	v_add_f32_e32 v250, v131, v250
	s_waitcnt lgkmcnt(2)
	v_mfma_f32_32x32x16_bf16 v[144:159], v[238:241], v[180:183], v[144:159]
	v_mfma_f32_32x32x16_bf16 v[144:159], v[242:245], v[176:179], v[144:159]
	ds_read_b128 v[238:241], v206 offset:0
	ds_read_b128 v[242:245], v207 offset:0
	s_add_i32 m0, s34, 0x6000
	s_nop 0
	global_load_lds_dwordx4 v223, s[86:87] sc1
	v_exp_f32_e32 v136, v136
	v_exp_f32_e32 v137, v137
	v_exp_f32_e32 v138, v138
	v_exp_f32_e32 v139, v139
	v_add_f32_e32 v250, v132, v250
	v_add_f32_e32 v250, v133, v250
	v_add_f32_e32 v250, v134, v250
	v_add_f32_e32 v250, v135, v250
	s_waitcnt lgkmcnt(2)
	v_mfma_f32_32x32x16_bf16 v[144:159], v[230:233], v[172:175], v[144:159]
	v_mfma_f32_32x32x16_bf16 v[144:159], v[234:237], v[168:171], v[144:159]
	v_exp_f32_e32 v140, v140
	v_exp_f32_e32 v141, v141
	v_exp_f32_e32 v142, v142
	v_exp_f32_e32 v143, v143
	v_add_f32_e32 v250, v136, v250
	v_add_f32_e32 v250, v137, v250
	v_add_f32_e32 v250, v138, v250
	v_add_f32_e32 v250, v139, v250
	v_cvt_pk_bf16_f32 v230, v128, v129
	v_cvt_pk_bf16_f32 v231, v130, v131
	v_cvt_pk_bf16_f32 v232, v132, v133
	v_cvt_pk_bf16_f32 v233, v134, v135
	s_waitcnt lgkmcnt(0)
	v_mfma_f32_32x32x16_bf16 v[144:159], v[238:241], v[164:167], v[144:159]
	v_mfma_f32_32x32x16_bf16 v[144:159], v[242:245], v[160:163], v[144:159]
	v_add_u32_e32 v249, s84, v218
	s_add_i32 s85, s84, 0x8000
	s_cmp_eq_u32 s85, 0x18000
	s_cselect_b32 s85, 0, s85
	ds_read_b64_tr_b16 v[238:239], v249 offset:0
	ds_read_b64_tr_b16 v[240:241], v249 offset:2048
	ds_read_b64_tr_b16 v[242:243], v249 offset:512
	ds_read_b64_tr_b16 v[244:245], v249 offset:2560
	ds_read_b64_tr_b16 v[128:129], v249 offset:4096
	ds_read_b64_tr_b16 v[130:131], v249 offset:6144
	ds_read_b64_tr_b16 v[132:133], v249 offset:4608
	ds_read_b64_tr_b16 v[134:135], v249 offset:6656
	v_add_f32_e32 v250, v140, v250
	v_add_f32_e32 v250, v141, v250
	v_add_f32_e32 v250, v142, v250
	v_add_f32_e32 v250, v143, v250
	v_cvt_pk_bf16_f32 v234, v136, v137
	v_cvt_pk_bf16_f32 v235, v138, v139
	v_cvt_pk_bf16_f32 v236, v140, v141
	v_cvt_pk_bf16_f32 v237, v142, v143
	v_add_f32_e32 v219, v219, v250
	ds_read_b64_tr_b16 v[136:137], v249 offset:1024
	ds_read_b64_tr_b16 v[138:139], v249 offset:3072
	ds_read_b64_tr_b16 v[140:141], v249 offset:1536
	ds_read_b64_tr_b16 v[142:143], v249 offset:3584
	s_waitcnt lgkmcnt(8)
	v_mfma_f32_32x32x16_bf16 v[112:127], v[230:233], v[238:241], v[112:127]
	v_mfma_f32_32x32x16_bf16 v[96:111], v[230:233], v[242:245], v[96:111]
	ds_read_b64_tr_b16 v[238:239], v249 offset:5120
	ds_read_b64_tr_b16 v[240:241], v249 offset:7168
	ds_read_b64_tr_b16 v[242:243], v249 offset:5632
	ds_read_b64_tr_b16 v[244:245], v249 offset:7680
	s_add_i32 s30, s85, s34
	s_add_i32 m0, s30, 0x8000
	s_nop 0
	global_load_lds_dwordx4 v222, s[2:3] sc1
	s_waitcnt lgkmcnt(8)
	v_mfma_f32_32x32x16_bf16 v[112:127], v[234:237], v[128:131], v[112:127]
	v_mfma_f32_32x32x16_bf16 v[96:111], v[234:237], v[132:135], v[96:111]
	ds_read_b64_tr_b16 v[128:129], v249 offset:16384
	ds_read_b64_tr_b16 v[130:131], v249 offset:18432
	ds_read_b64_tr_b16 v[132:133], v249 offset:16896
	ds_read_b64_tr_b16 v[134:135], v249 offset:18944
	s_add_i32 s30, s85, s34
	s_add_i32 m0, s30, 0xa000
	s_nop 0
	global_load_lds_dwordx4 v221, s[2:3] sc1
	s_waitcnt lgkmcnt(8)
	v_mfma_f32_32x32x16_bf16 v[80:95], v[230:233], v[136:139], v[80:95]
	v_mfma_f32_32x32x16_bf16 v[64:79], v[230:233], v[140:143], v[64:79]
	ds_read_b64_tr_b16 v[136:137], v249 offset:20480
	ds_read_b64_tr_b16 v[138:139], v249 offset:22528
	ds_read_b64_tr_b16 v[140:141], v249 offset:20992
	ds_read_b64_tr_b16 v[142:143], v249 offset:23040
	s_add_i32 s30, s85, s34
	s_add_i32 m0, s30, 0xc000
	s_nop 0
	global_load_lds_dwordx4 v246, s[2:3] sc1
	s_waitcnt lgkmcnt(8)
	v_mfma_f32_32x32x16_bf16 v[80:95], v[234:237], v[238:241], v[80:95]
	v_mfma_f32_32x32x16_bf16 v[64:79], v[234:237], v[242:245], v[64:79]
	ds_read_b64_tr_b16 v[238:239], v249 offset:17408
	ds_read_b64_tr_b16 v[240:241], v249 offset:19456
	ds_read_b64_tr_b16 v[242:243], v249 offset:17920
	ds_read_b64_tr_b16 v[244:245], v249 offset:19968
	s_add_i32 s30, s85, s34
	s_add_i32 m0, s30, 0xe000
	s_nop 0
	global_load_lds_dwordx4 v247, s[2:3] sc1
	s_waitcnt lgkmcnt(8)
	v_mfma_f32_32x32x16_bf16 v[32:47], v[230:233], v[128:131], v[32:47]
	v_mfma_f32_32x32x16_bf16 v[16:31], v[230:233], v[132:135], v[16:31]
	ds_read_b64_tr_b16 v[128:129], v249 offset:21504
	ds_read_b64_tr_b16 v[130:131], v249 offset:23552
	ds_read_b64_tr_b16 v[132:133], v249 offset:22016
	ds_read_b64_tr_b16 v[134:135], v249 offset:24064
	s_waitcnt lgkmcnt(8)
	v_mfma_f32_32x32x16_bf16 v[32:47], v[234:237], v[136:139], v[32:47]
	v_mfma_f32_32x32x16_bf16 v[16:31], v[234:237], v[140:143], v[16:31]
	s_waitcnt lgkmcnt(0)
	v_mfma_f32_32x32x16_bf16 v[48:63], v[230:233], v[238:241], v[48:63]
	s_waitcnt vmcnt(0)
	s_barrier
	s_add_u32 s86, s86, 0x4000
	s_addc_u32 s87, s87, 0
	s_add_u32 s2, s2, 0x8000
	s_addc_u32 s3, s3, 0
	v_mfma_f32_32x32x16_bf16 v[0:15], v[230:233], v[242:245], v[0:15]
	v_mfma_f32_32x32x16_bf16 v[48:63], v[234:237], v[128:131], v[48:63]
	v_mfma_f32_32x32x16_bf16 v[0:15], v[234:237], v[132:135], v[0:15]
	s_add_i32 s84, s84, 0x8000
	s_cmp_eq_u32 s84, 0x18000
	s_cselect_b32 s84, 0, s84
	s_add_i32 s40, s40, 1
	s_cmpk_eq_i32 s40, 0x82
	s_cbranch_scc0 .LBB0_1023
	s_barrier
	s_branch .Lattn_join_m1
